# sample-attn K-pass tail rewrite: hoisted masked Q frags, permlane-swap row reduction, early rope-key/KRSS reads, counted lgkmcnt
# speedup vs baseline: 1.0143x; 1.0143x over previous
.LBB0_1865:
	ds_read_b128 v[146:149], v207
	ds_read_b128 v[150:153], v207 offset:64
	s_bitcmp1_b32 s78, 3
	s_cselect_b32 s48, 0x1800, 0
	v_add_u32_e32 v214, s48, v192
	s_mov_b32 s50, 16
	v_add_u32_e32 v215, v214, v193
	v_mov_b32_e32 v216, v206
	v_mov_b32_e32 v217, v195
	v_mov_b32_e32 v218, v0
	v_mov_b32_e32 v219, v194
	ds_read2_b64 v[174:177], v215 offset1:4
	ds_read2_b64 v[246:249], v215 offset0:8 offset1:12
	s_waitcnt lgkmcnt(0)
	v_cndmask_b32_e64 v174, 0, v174, s[4:5]
	v_cndmask_b32_e64 v175, 0, v175, s[4:5]
	v_cndmask_b32_e64 v176, 0, v176, s[4:5]
	v_cndmask_b32_e64 v177, 0, v177, s[4:5]
	v_cndmask_b32_e64 v246, 0, v246, s[4:5]
	v_cndmask_b32_e64 v247, 0, v247, s[4:5]
	v_cndmask_b32_e64 v248, 0, v248, s[4:5]
	v_cndmask_b32_e64 v249, 0, v249, s[4:5]
.LBB0_1867:
	v_add_u32_e32 v204, 0, v216
	v_add_u32_e32 v154, 0x12080, v204
	v_add_u32_e32 v196, 0x120c0, v204
	ds_read_b128 v[154:157], v154
	ds_read_b128 v[196:199], v196
	v_and_or_b32 v200, s50, 48, v183
	v_mad_u32_u24 v205, v200, s77, v185
	v_add_u32_e32 v237, 0x12100, v204
	v_mfma_f32_16x16x32_bf16 v[200:203], v[2:5], v[146:149], 0
	ds_read_b128 v[238:241], v237
	v_mfma_f32_16x16x32_bf16 v[220:223], v[6:9], v[146:149], 0
	v_mfma_f32_16x16x32_bf16 v[224:227], v[10:13], v[146:149], 0
	v_mfma_f32_16x16x32_bf16 v[146:149], v[14:17], v[146:149], 0
	v_mfma_f32_16x16x32_bf16 v[200:203], v[18:21], v[150:153], v[200:203]
	v_mfma_f32_16x16x32_bf16 v[220:223], v[22:25], v[150:153], v[220:223]
	v_mfma_f32_16x16x32_bf16 v[224:227], v[26:29], v[150:153], v[224:227]
	v_mfma_f32_16x16x32_bf16 v[146:149], v[30:33], v[150:153], v[146:149]
	v_add_u32_e32 v150, 0x12140, v204
	ds_read_b128 v[150:153], v150
	s_waitcnt lgkmcnt(2)
	v_mfma_f32_16x16x32_bf16 v[200:203], v[34:37], v[154:157], v[200:203]
	v_mfma_f32_16x16x32_bf16 v[220:223], v[38:41], v[154:157], v[220:223]
	v_mfma_f32_16x16x32_bf16 v[224:227], v[42:45], v[154:157], v[224:227]
	v_mfma_f32_16x16x32_bf16 v[146:149], v[46:49], v[154:157], v[146:149]
	v_add_u32_e32 v154, 0x12180, v204
	ds_read_b128 v[154:157], v154
	v_mfma_f32_16x16x32_bf16 v[200:203], v[50:53], v[196:199], v[200:203]
	v_mfma_f32_16x16x32_bf16 v[220:223], v[54:57], v[196:199], v[220:223]
	v_mfma_f32_16x16x32_bf16 v[224:227], v[58:61], v[196:199], v[224:227]
	v_mfma_f32_16x16x32_bf16 v[146:149], v[62:65], v[196:199], v[146:149]
	v_add_u32_e32 v196, 0x121c0, v204
	ds_read_b128 v[196:199], v196
	s_waitcnt lgkmcnt(3)
	v_mfma_f32_16x16x32_bf16 v[200:203], v[66:69], v[238:241], v[200:203]
	v_mfma_f32_16x16x32_bf16 v[220:223], v[70:73], v[238:241], v[220:223]
	v_mfma_f32_16x16x32_bf16 v[224:227], v[74:77], v[238:241], v[224:227]
	v_mfma_f32_16x16x32_bf16 v[238:241], v[78:81], v[238:241], v[146:149]
	s_nop 2
	ds_read_b128 v[146:149], v205
	s_waitcnt lgkmcnt(3)
	v_mfma_f32_16x16x32_bf16 v[200:203], v[82:85], v[150:153], v[200:203]
	v_mfma_f32_16x16x32_bf16 v[220:223], v[86:89], v[150:153], v[220:223]
	v_mfma_f32_16x16x32_bf16 v[224:227], v[90:93], v[150:153], v[224:227]
	v_mfma_f32_16x16x32_bf16 v[238:241], v[94:97], v[150:153], v[238:241]
	ds_read_b128 v[150:153], v205 offset:64
	s_waitcnt lgkmcnt(3)
	v_mfma_f32_16x16x32_bf16 v[200:203], v[98:101], v[154:157], v[200:203]
	v_mfma_f32_16x16x32_bf16 v[220:223], v[102:105], v[154:157], v[220:223]
	v_mfma_f32_16x16x32_bf16 v[224:227], v[106:109], v[154:157], v[224:227]
	v_mfma_f32_16x16x32_bf16 v[154:157], v[110:113], v[154:157], v[238:241]
	s_waitcnt lgkmcnt(2)
	v_mfma_f32_16x16x32_bf16 v[220:223], v[118:121], v[196:199], v[220:223]
	v_mfma_f32_16x16x32_bf16 v[154:157], v[126:129], v[196:199], v[154:157]
	v_mfma_f32_16x16x32_bf16 v[200:203], v[114:117], v[196:199], v[200:203]
	v_mfma_f32_16x16x32_bf16 v[224:227], v[122:125], v[196:199], v[224:227]
	ds_read_b128 v[196:199], v217
	ds_read_b128 v[242:245], v214 offset:128
	ds_read_b32 v255, v218
	s_nop 4
	v_mul_f32_e32 v204, v201, v201
	v_mul_f32_e32 v205, v203, v203
	v_fmac_f32_e32 v204, v200, v200
	v_fmac_f32_e32 v205, v202, v202
	v_add_f32_e32 v204, v204, v205
	v_mul_f32_e32 v205, v221, v221
	v_mul_f32_e32 v237, v223, v223
	v_fmac_f32_e32 v205, v220, v220
	v_fmac_f32_e32 v237, v222, v222
	v_add_f32_e32 v205, v205, v237
	v_add_f32_e32 v204, v204, v205
	v_mul_f32_e32 v205, v225, v225
	v_mul_f32_e32 v237, v227, v227
	v_fmac_f32_e32 v205, v224, v224
	v_fmac_f32_e32 v237, v226, v226
	v_add_f32_e32 v205, v205, v237
	v_add_f32_e32 v204, v204, v205
	v_mul_f32_e32 v205, v155, v155
	v_mul_f32_e32 v237, v157, v157
	v_fmac_f32_e32 v205, v154, v154
	v_fmac_f32_e32 v237, v156, v156
	v_add_f32_e32 v205, v205, v237
	v_add_f32_e32 v204, v204, v205
	v_mov_b32_e32 v205, v204
	v_cvt_pk_bf16_f32 v200, v200, v201
	v_cvt_pk_bf16_f32 v201, v202, v203
	v_permlane16_swap_b32_e32 v204, v205
	v_cvt_pk_bf16_f32 v202, v220, v221
	v_cvt_pk_bf16_f32 v203, v222, v223
	v_add_f32_e32 v204, v204, v205
	v_mov_b32_e32 v205, v204
	v_cvt_pk_bf16_f32 v220, v224, v225
	v_cvt_pk_bf16_f32 v221, v226, v227
	v_permlane32_swap_b32_e32 v204, v205
	v_cvt_pk_bf16_f32 v222, v154, v155
	v_cvt_pk_bf16_f32 v223, v156, v157
	v_add_f32_e32 v204, v204, v205
	s_waitcnt lgkmcnt(0)
	v_cndmask_b32_e64 v242, 0, v242, s[4:5]
	v_cndmask_b32_e64 v243, 0, v243, s[4:5]
	v_mfma_f32_16x16x32_bf16 v[238:241], v[174:177], v[200:203], 0
	v_cndmask_b32_e64 v244, 0, v244, s[4:5]
	v_cndmask_b32_e64 v245, 0, v245, s[4:5]
	v_mfma_f32_16x16x32_bf16 v[238:241], v[246:249], v[220:223], v[238:241]
	v_add_f32_e32 v255, v204, v255
	v_fmamk_f32 v255, v255, 0x3c2aaaab, v231
	v_mfma_f32_16x16x32_bf16 v[238:241], v[242:245], v[196:199], v[238:241]
	v_rsq_f32_e32 v255, v255
	v_add_u32_e32 v205, 0x1cb80, v219
	s_add_i32 s50, s50, 16
	v_add_u32_e32 v219, 64, v219
	v_add_u32_e32 v218, 64, v218
	v_add_u32_e32 v217, 0x500, v217
	v_add_u32_e32 v216, 0x2100, v216
	s_and_saveexec_b64 s[48:49], s[6:7]
	s_nop 1
	v_mul_f32_e32 v200, v238, v255
	v_mul_f32_e32 v201, v239, v255
	v_mul_f32_e32 v202, v240, v255
	v_mul_f32_e32 v203, v241, v255
	ds_write_b32 v205, v200
	ds_write_b32 v205, v201 offset:272
	ds_write_b32 v205, v202 offset:544
	ds_write_b32 v205, v203 offset:816
	s_mov_b64 exec, s[48:49]
	s_cmpk_eq_i32 s50, 0x50
	s_cbranch_scc0 .LBB0_1867

.LBB0_1875:
	s_waitcnt vmcnt(0)
	s_barrier
	ds_read_b128 v[150:153], v169
	ds_read_b128 v[154:157], v169 offset:8192
	ds_read_b128 v[196:199], v169 offset:16384
	ds_read_b128 v[200:203], v169 offset:24576
	s_waitcnt lgkmcnt(3)
	v_cvt_pk_bf16_f32 v150, v150, v151
	v_cvt_pk_bf16_f32 v151, v152, v153
	ds_write_b64 v171, v[150:151]
	s_waitcnt lgkmcnt(3)
	v_cvt_pk_bf16_f32 v150, v154, v155
	v_cvt_pk_bf16_f32 v151, v156, v157
	ds_write_b64 v171, v[150:151] offset:4224
	s_waitcnt lgkmcnt(3)
	v_cvt_pk_bf16_f32 v150, v196, v197
	v_cvt_pk_bf16_f32 v151, v198, v199
	ds_write_b64 v171, v[150:151] offset:8448
	s_waitcnt lgkmcnt(3)
	v_cvt_pk_bf16_f32 v150, v200, v201
	v_cvt_pk_bf16_f32 v151, v202, v203
	ds_write_b64 v171, v[150:151] offset:12672
	ds_read_b128 v[150:153], v169 offset:32768
	ds_read_b128 v[154:157], v169 offset:40960
	ds_read_b128 v[196:199], v169 offset:49152
	ds_read_b128 v[200:203], v169 offset:57344
	s_waitcnt lgkmcnt(3)
	v_cvt_pk_bf16_f32 v150, v150, v151
	v_cvt_pk_bf16_f32 v151, v152, v153
	ds_write_b64 v171, v[150:151] offset:16896
	s_waitcnt lgkmcnt(3)
	v_cvt_pk_bf16_f32 v150, v154, v155
	v_cvt_pk_bf16_f32 v151, v156, v157
	ds_write_b64 v171, v[150:151] offset:21120
	s_waitcnt lgkmcnt(3)
	v_cvt_pk_bf16_f32 v150, v196, v197
	v_cvt_pk_bf16_f32 v151, v198, v199
	ds_write_b64 v171, v[150:151] offset:25344
	s_waitcnt lgkmcnt(3)
	v_cvt_pk_bf16_f32 v150, v200, v201
	v_cvt_pk_bf16_f32 v151, v202, v203
	ds_write_b64 v171, v[150:151] offset:29568
	ds_read_b128 v[150:153], v181
	s_waitcnt lgkmcnt(0)
	v_cvt_pk_bf16_f32 v150, v150, v151
	v_cvt_pk_bf16_f32 v151, v152, v153
	ds_write_b64 v182, v[150:151]
	v_and_b32_e32 v149, 0xffff0000, v150
	v_lshlrev_b32_e32 v147, 16, v150
	v_mul_f32_e32 v149, v149, v149
	v_fmac_f32_e32 v149, v147, v147
	v_and_b32_e32 v147, 0xffff0000, v151
	v_lshlrev_b32_e32 v150, 16, v151
	v_mul_f32_e32 v147, v147, v147
	v_fmac_f32_e32 v147, v150, v150
	v_add_f32_e32 v147, v149, v147
	s_nop 1
	v_add_f32_dpp v147, v147, v147 quad_perm:[1,0,3,2] row_mask:0xf bank_mask:0xf bound_ctrl:1
	s_nop 1
	v_add_f32_dpp v147, v147, v147 quad_perm:[2,3,0,1] row_mask:0xf bank_mask:0xf bound_ctrl:1
	s_nop 1
	v_mov_b32_dpp v149, v147 row_half_mirror row_mask:0xf bank_mask:0xf bound_ctrl:1
	s_and_saveexec_b64 s[50:51], s[2:3]
	v_add_f32_e32 v147, v147, v149
	ds_write_b32 v189, v147
	s_or_b64 exec, exec, s[50:51]
	s_add_i32 s78, s78, 1
	s_cmp_ge_i32 s78, s62
	s_cselect_b64 s[50:51], -1, 0
	s_or_b64 s[48:49], s[48:49], s[50:51]
	s_nor_b64 s[50:51], s[0:1], s[48:49]
	s_and_saveexec_b64 s[48:49], s[50:51]
	s_cbranch_execz .LBB0_1862
	s_add_i32 s47, s81, 1
	s_mul_i32 s50, s47, s24
	s_add_i32 s50, s50, s25
	s_ashr_i32 s50, s50, 3
	s_and_b32 s50, s50, -4
	v_add_u32_e32 v147, s50, v190
	v_ashrrev_i32_e32 v149, 31, v147
	v_lshl_or_b32 v147, v147, 3, v170
	v_mad_u64_u32 v[150:151], s[50:51], v147, s33, v[172:173]
	v_mad_i32_i24 v151, v149, s33, v151
	global_load_dwordx4 v[150:153], v[150:151], off
	s_bitcmp1_b32 s47, 0
	s_cselect_b32 s47, 0x1800, 0
	v_add_u32_e32 v147, s47, v191
	s_waitcnt vmcnt(0)
	ds_write_b128 v147, v[150:153]
	s_branch .LBB0_1862

	.amdhsa_kernel _Z6mk_fwd4Args
		.amdhsa_group_segment_fixed_size 0
		.amdhsa_private_segment_fixed_size 0
		.amdhsa_kernarg_size 600
		.amdhsa_user_sgpr_count 2
		.amdhsa_user_sgpr_dispatch_ptr 0
		.amdhsa_user_sgpr_queue_ptr 0
		.amdhsa_user_sgpr_kernarg_segment_ptr 1
		.amdhsa_user_sgpr_dispatch_id 0
		.amdhsa_user_sgpr_kernarg_preload_length 0
		.amdhsa_user_sgpr_kernarg_preload_offset 0
		.amdhsa_user_sgpr_private_segment_size 0
		.amdhsa_uses_dynamic_stack 0
		.amdhsa_enable_private_segment 0
		.amdhsa_system_sgpr_workgroup_id_x 1
		.amdhsa_system_sgpr_workgroup_id_y 0
		.amdhsa_system_sgpr_workgroup_id_z 0
		.amdhsa_system_sgpr_workgroup_info 0
		.amdhsa_system_vgpr_workitem_id 0
		.amdhsa_next_free_vgpr 256
		.amdhsa_next_free_sgpr 100
		.amdhsa_accum_offset 256
		.amdhsa_reserve_vcc 1
		.amdhsa_float_round_mode_32 0
		.amdhsa_float_round_mode_16_64 0
		.amdhsa_float_denorm_mode_32 3
		.amdhsa_float_denorm_mode_16_64 3
		.amdhsa_dx10_clamp 1
		.amdhsa_ieee_mode 1
		.amdhsa_fp16_overflow 0
		.amdhsa_tg_split 0
		.amdhsa_exception_fp_ieee_invalid_op 0
		.amdhsa_exception_fp_denorm_src 0
		.amdhsa_exception_fp_ieee_div_zero 0
		.amdhsa_exception_fp_ieee_overflow 0
		.amdhsa_exception_fp_ieee_underflow 0
		.amdhsa_exception_fp_ieee_inexact 0
		.amdhsa_exception_int_div_zero 0
	.end_amdhsa_kernel

amdhsa.kernels:
  - .agpr_count:     0
    .args:
      - .offset:         0
        .size:           344
        .value_kind:     by_value
      - .offset:         344
        .size:           4
        .value_kind:     hidden_block_count_x
      - .offset:         348
        .size:           4
        .value_kind:     hidden_block_count_y
      - .offset:         352
        .size:           4
        .value_kind:     hidden_block_count_z
      - .offset:         356
        .size:           2
        .value_kind:     hidden_group_size_x
      - .offset:         358
        .size:           2
        .value_kind:     hidden_group_size_y
      - .offset:         360
        .size:           2
        .value_kind:     hidden_group_size_z
      - .offset:         362
        .size:           2
        .value_kind:     hidden_remainder_x
      - .offset:         364
        .size:           2
        .value_kind:     hidden_remainder_y
      - .offset:         366
        .size:           2
        .value_kind:     hidden_remainder_z
      - .offset:         384
        .size:           8
        .value_kind:     hidden_global_offset_x
      - .offset:         392
        .size:           8
        .value_kind:     hidden_global_offset_y
      - .offset:         400
        .size:           8
        .value_kind:     hidden_global_offset_z
      - .offset:         408
        .size:           2
        .value_kind:     hidden_grid_dims
      - .offset:         464
        .size:           4
        .value_kind:     hidden_dynamic_lds_size
    .group_segment_fixed_size: 0
    .kernarg_segment_align: 8
    .kernarg_segment_size: 600
    .language:       OpenCL C
    .language_version:
      - 2
      - 0
    .max_flat_workgroup_size: 512
    .name:           _Z6mk_fwd4Args
    .private_segment_fixed_size: 0
    .sgpr_count:     106
    .sgpr_spill_count: 209
    .symbol:         _Z6mk_fwd4Args.kd
    .uniform_work_group_size: 1
    .uses_dynamic_stack: false
    .vgpr_count:     256
    .vgpr_spill_count: 0
    .wavefront_size: 64
